# FF1 K-loop SP2 phases: LDS-DMA issued before the A-fragment ds_reads
# baseline (speedup 1.0000x reference)
.LBB0_211:
	s_add_i32 s73, s58, 2
	s_add_u32 s74, s56, 0x80
	s_addc_u32 s59, s57, 0
	s_add_i32 s78, 0, 0x10000
	s_cmp_eq_u32 s63, s58
	s_cselect_b32 s59, s51, s59
	s_cselect_b32 s58, s55, s74
	v_add_u32_e32 v0, s78, v146
	s_cselect_b32 s75, s45, s72
	s_cselect_b32 s74, s44, s67
	s_add_i32 s80, 0, 0x14000
	ds_read_b128 v[148:151], v0
	ds_read_b128 v[152:155], v0 offset:1024
	ds_read_b128 v[156:159], v0 offset:2048
	ds_read_b128 v[160:163], v0 offset:3072
	v_add_u32_e32 v0, s80, v146
	ds_read_b128 v[164:167], v0
	ds_read_b128 v[168:171], v0 offset:1024
	ds_read_b128 v[172:175], v0 offset:2048
	ds_read_b128 v[176:179], v0 offset:3072
	v_lshl_add_u64 v[142:143], s[56:57], 0, v[136:137]
	s_mov_b32 m0, s31
	global_load_lds_dwordx4 v[142:143], off
	v_lshl_add_u64 v[142:143], s[56:57], 0, v[132:133]
	s_mov_b32 m0, s53
	s_nop 0
	global_load_lds_dwordx4 v[142:143], off
	v_lshl_add_u64 v[142:143], s[56:57], 0, v[138:139]
	s_add_i32 m0, s27, 0xc000
	s_nop 0
	global_load_lds_dwordx4 v[142:143], off
	v_lshl_add_u64 v[142:143], s[56:57], 0, v[140:141]
	s_add_i32 m0, s27, 0xe000
	s_nop 0
	global_load_lds_dwordx4 v[142:143], off
	ds_read_b128 v[180:183], v147
	ds_read_b128 v[184:187], v147 offset:1024
	ds_read_b128 v[200:203], v147 offset:2048
	ds_read_b128 v[204:207], v147 offset:3072
	ds_read_b128 v[208:211], v147 offset:4096
	ds_read_b128 v[212:215], v147 offset:5120
	ds_read_b128 v[216:219], v147 offset:6144
	ds_read_b128 v[220:223], v147 offset:7168
	s_waitcnt vmcnt(8)
	s_waitcnt lgkmcnt(0)
	s_barrier
	s_setprio 1
	s_waitcnt lgkmcnt(0)
	v_mfma_f32_16x16x32_bf16 v[122:125], v[148:151], v[180:183], v[122:125]
	v_mfma_f32_16x16x32_bf16 v[126:129], v[156:159], v[180:183], v[126:129]
	v_mfma_f32_16x16x32_bf16 v[110:113], v[148:151], v[200:203], v[110:113]
	v_mfma_f32_16x16x32_bf16 v[106:109], v[156:159], v[200:203], v[106:109]
	v_mfma_f32_16x16x32_bf16 v[94:97], v[148:151], v[208:211], v[94:97]
	v_mfma_f32_16x16x32_bf16 v[90:93], v[156:159], v[208:211], v[90:93]
	v_mfma_f32_16x16x32_bf16 v[78:81], v[148:151], v[216:219], v[78:81]
	v_mfma_f32_16x16x32_bf16 v[74:77], v[156:159], v[216:219], v[74:77]
	v_mfma_f32_16x16x32_bf16 v[122:125], v[152:155], v[184:187], v[122:125]
	v_mfma_f32_16x16x32_bf16 v[126:129], v[160:163], v[184:187], v[126:129]
	v_mfma_f32_16x16x32_bf16 v[110:113], v[152:155], v[204:207], v[110:113]
	v_mfma_f32_16x16x32_bf16 v[106:109], v[160:163], v[204:207], v[106:109]
	v_mfma_f32_16x16x32_bf16 v[94:97], v[152:155], v[212:215], v[94:97]
	v_mfma_f32_16x16x32_bf16 v[90:93], v[160:163], v[212:215], v[90:93]
	v_mfma_f32_16x16x32_bf16 v[78:81], v[152:155], v[220:223], v[78:81]
	v_mfma_f32_16x16x32_bf16 v[74:77], v[160:163], v[220:223], v[74:77]
	s_setprio 0
	s_setprio 1
	v_mfma_f32_16x16x32_bf16 v[118:121], v[164:167], v[180:183], v[118:121]
	v_mfma_f32_16x16x32_bf16 v[114:117], v[172:175], v[180:183], v[114:117]
	v_mfma_f32_16x16x32_bf16 v[102:105], v[164:167], v[200:203], v[102:105]
	v_mfma_f32_16x16x32_bf16 v[98:101], v[172:175], v[200:203], v[98:101]
	v_mfma_f32_16x16x32_bf16 v[86:89], v[164:167], v[208:211], v[86:89]
	v_mfma_f32_16x16x32_bf16 v[82:85], v[172:175], v[208:211], v[82:85]
	v_mfma_f32_16x16x32_bf16 v[70:73], v[164:167], v[216:219], v[70:73]
	v_mfma_f32_16x16x32_bf16 v[66:69], v[172:175], v[216:219], v[66:69]
	v_mfma_f32_16x16x32_bf16 v[118:121], v[168:171], v[184:187], v[118:121]
	v_mfma_f32_16x16x32_bf16 v[114:117], v[176:179], v[184:187], v[114:117]
	v_mfma_f32_16x16x32_bf16 v[102:105], v[168:171], v[204:207], v[102:105]
	v_mfma_f32_16x16x32_bf16 v[98:101], v[176:179], v[204:207], v[98:101]
	v_mfma_f32_16x16x32_bf16 v[86:89], v[168:171], v[212:215], v[86:89]
	v_mfma_f32_16x16x32_bf16 v[82:85], v[176:179], v[212:215], v[82:85]
	v_mfma_f32_16x16x32_bf16 v[70:73], v[168:171], v[220:223], v[70:73]
	v_mfma_f32_16x16x32_bf16 v[66:69], v[176:179], v[220:223], v[66:69]
	s_setprio 0
	s_barrier
	s_add_i32 s78, s78, s5
	v_lshl_add_u64 v[142:143], s[74:75], 0, v[134:135]
	s_mov_b32 m0, s78
	s_nop 0
	global_load_lds_dwordx4 v[142:143], off
	s_add_i32 m0, s78, 0x2000
	v_lshl_add_u64 v[188:189], s[74:75], 0, v[130:131]
	s_add_u32 s74, s74, s6
	s_addc_u32 s75, s75, s7
	s_add_i32 s78, s80, s5
	global_load_lds_dwordx4 v[188:189], off
	v_lshl_add_u64 v[224:225], s[74:75], 0, v[134:135]
	s_mov_b32 m0, s78
	v_lshl_add_u64 v[226:227], s[74:75], 0, v[130:131]
	global_load_lds_dwordx4 v[224:225], off
	s_add_i32 m0, s78, 0x2000
	v_lshl_add_u64 v[228:229], s[58:59], 0, v[136:137]
	global_load_lds_dwordx4 v[226:227], off
	v_lshl_add_u64 v[230:231], s[58:59], 0, v[132:133]
	ds_read_b128 v[180:183], v147 offset:16384
	ds_read_b128 v[184:187], v147 offset:17408
	ds_read_b128 v[200:203], v147 offset:18432
	ds_read_b128 v[204:207], v147 offset:19456
	ds_read_b128 v[208:211], v147 offset:20480
	ds_read_b128 v[212:215], v147 offset:21504
	ds_read_b128 v[216:219], v147 offset:22528
	ds_read_b128 v[220:223], v147 offset:23552
	s_waitcnt vmcnt(6)
	s_waitcnt lgkmcnt(0)
	s_barrier
	s_setprio 1
	s_waitcnt lgkmcnt(0)
	v_mfma_f32_16x16x32_bf16 v[62:65], v[148:151], v[180:183], v[62:65]
	v_mfma_f32_16x16x32_bf16 v[58:61], v[156:159], v[180:183], v[58:61]
	v_mfma_f32_16x16x32_bf16 v[46:49], v[148:151], v[200:203], v[46:49]
	v_mfma_f32_16x16x32_bf16 v[42:45], v[156:159], v[200:203], v[42:45]
	v_mfma_f32_16x16x32_bf16 v[30:33], v[148:151], v[208:211], v[30:33]
	v_mfma_f32_16x16x32_bf16 v[26:29], v[156:159], v[208:211], v[26:29]
	v_mfma_f32_16x16x32_bf16 v[14:17], v[148:151], v[216:219], v[14:17]
	v_mfma_f32_16x16x32_bf16 v[10:13], v[156:159], v[216:219], v[10:13]
	v_mfma_f32_16x16x32_bf16 v[62:65], v[152:155], v[184:187], v[62:65]
	v_mfma_f32_16x16x32_bf16 v[58:61], v[160:163], v[184:187], v[58:61]
	v_mfma_f32_16x16x32_bf16 v[46:49], v[152:155], v[204:207], v[46:49]
	v_mfma_f32_16x16x32_bf16 v[42:45], v[160:163], v[204:207], v[42:45]
	v_mfma_f32_16x16x32_bf16 v[30:33], v[152:155], v[212:215], v[30:33]
	v_mfma_f32_16x16x32_bf16 v[26:29], v[160:163], v[212:215], v[26:29]
	v_mfma_f32_16x16x32_bf16 v[14:17], v[152:155], v[220:223], v[14:17]
	v_mfma_f32_16x16x32_bf16 v[10:13], v[160:163], v[220:223], v[10:13]
	s_setprio 0
	s_setprio 1
	v_mfma_f32_16x16x32_bf16 v[54:57], v[164:167], v[180:183], v[54:57]
	v_mfma_f32_16x16x32_bf16 v[50:53], v[172:175], v[180:183], v[50:53]
	v_mfma_f32_16x16x32_bf16 v[38:41], v[164:167], v[200:203], v[38:41]
	v_mfma_f32_16x16x32_bf16 v[34:37], v[172:175], v[200:203], v[34:37]
	v_mfma_f32_16x16x32_bf16 v[22:25], v[164:167], v[208:211], v[22:25]
	v_mfma_f32_16x16x32_bf16 v[18:21], v[172:175], v[208:211], v[18:21]
	v_mfma_f32_16x16x32_bf16 v[6:9], v[164:167], v[216:219], v[6:9]
	v_mfma_f32_16x16x32_bf16 v[2:5], v[172:175], v[216:219], v[2:5]
	v_mfma_f32_16x16x32_bf16 v[54:57], v[168:171], v[184:187], v[54:57]
	v_mfma_f32_16x16x32_bf16 v[50:53], v[176:179], v[184:187], v[50:53]
	v_mfma_f32_16x16x32_bf16 v[38:41], v[168:171], v[204:207], v[38:41]
	v_mfma_f32_16x16x32_bf16 v[34:37], v[176:179], v[204:207], v[34:37]
	v_mfma_f32_16x16x32_bf16 v[22:25], v[168:171], v[212:215], v[22:25]
	v_mfma_f32_16x16x32_bf16 v[18:21], v[176:179], v[212:215], v[18:21]
	v_mfma_f32_16x16x32_bf16 v[6:9], v[168:171], v[220:223], v[6:9]
	v_mfma_f32_16x16x32_bf16 v[2:5], v[176:179], v[220:223], v[2:5]
	s_setprio 0
	s_barrier
	s_add_i32 s74, 0, 0x18000
	v_add_u32_e32 v0, s74, v146
	s_add_i32 s75, 0, 0x1c000
	ds_read_b128 v[148:151], v0
	ds_read_b128 v[152:155], v0 offset:1024
	ds_read_b128 v[156:159], v0 offset:2048
	ds_read_b128 v[160:163], v0 offset:3072
	v_add_u32_e32 v0, s75, v146
	ds_read_b128 v[164:167], v0
	ds_read_b128 v[168:171], v0 offset:1024
	ds_read_b128 v[172:175], v0 offset:2048
	ds_read_b128 v[176:179], v0 offset:3072
	s_add_u32 s58, s58, s2
	s_addc_u32 s59, s59, s3
	s_mov_b32 m0, s27
	v_lshl_add_u64 v[232:233], s[58:59], 0, v[136:137]
	s_nop 0
	global_load_lds_dwordx4 v[228:229], off
	s_mov_b32 m0, s28
	s_nop 0
	global_load_lds_dwordx4 v[230:231], off
	s_mov_b32 m0, s29
	s_nop 0
	global_load_lds_dwordx4 v[232:233], off
	v_lshl_add_u64 v[232:233], s[58:59], 0, v[132:133]
	s_mov_b32 m0, s30
	s_nop 0
	global_load_lds_dwordx4 v[232:233], off
	ds_read_b128 v[180:183], v147 offset:32768
	ds_read_b128 v[184:187], v147 offset:33792
	ds_read_b128 v[200:203], v147 offset:34816
	ds_read_b128 v[204:207], v147 offset:35840
	ds_read_b128 v[208:211], v147 offset:36864
	ds_read_b128 v[212:215], v147 offset:37888
	ds_read_b128 v[216:219], v147 offset:38912
	ds_read_b128 v[220:223], v147 offset:39936
	s_waitcnt vmcnt(8)
	s_waitcnt lgkmcnt(0)
	s_barrier
	s_setprio 1
	s_waitcnt lgkmcnt(0)
	v_mfma_f32_16x16x32_bf16 v[122:125], v[148:151], v[180:183], v[122:125]
	v_mfma_f32_16x16x32_bf16 v[126:129], v[156:159], v[180:183], v[126:129]
	v_mfma_f32_16x16x32_bf16 v[110:113], v[148:151], v[200:203], v[110:113]
	v_mfma_f32_16x16x32_bf16 v[106:109], v[156:159], v[200:203], v[106:109]
	v_mfma_f32_16x16x32_bf16 v[94:97], v[148:151], v[208:211], v[94:97]
	v_mfma_f32_16x16x32_bf16 v[90:93], v[156:159], v[208:211], v[90:93]
	v_mfma_f32_16x16x32_bf16 v[78:81], v[148:151], v[216:219], v[78:81]
	v_mfma_f32_16x16x32_bf16 v[74:77], v[156:159], v[216:219], v[74:77]
	v_mfma_f32_16x16x32_bf16 v[122:125], v[152:155], v[184:187], v[122:125]
	v_mfma_f32_16x16x32_bf16 v[126:129], v[160:163], v[184:187], v[126:129]
	v_mfma_f32_16x16x32_bf16 v[110:113], v[152:155], v[204:207], v[110:113]
	v_mfma_f32_16x16x32_bf16 v[106:109], v[160:163], v[204:207], v[106:109]
	v_mfma_f32_16x16x32_bf16 v[94:97], v[152:155], v[212:215], v[94:97]
	v_mfma_f32_16x16x32_bf16 v[90:93], v[160:163], v[212:215], v[90:93]
	v_mfma_f32_16x16x32_bf16 v[78:81], v[152:155], v[220:223], v[78:81]
	v_mfma_f32_16x16x32_bf16 v[74:77], v[160:163], v[220:223], v[74:77]
	s_setprio 0
	s_setprio 1
	v_mfma_f32_16x16x32_bf16 v[118:121], v[164:167], v[180:183], v[118:121]
	v_mfma_f32_16x16x32_bf16 v[114:117], v[172:175], v[180:183], v[114:117]
	v_mfma_f32_16x16x32_bf16 v[102:105], v[164:167], v[200:203], v[102:105]
	v_mfma_f32_16x16x32_bf16 v[98:101], v[172:175], v[200:203], v[98:101]
	v_mfma_f32_16x16x32_bf16 v[86:89], v[164:167], v[208:211], v[86:89]
	v_mfma_f32_16x16x32_bf16 v[82:85], v[172:175], v[208:211], v[82:85]
	v_mfma_f32_16x16x32_bf16 v[70:73], v[164:167], v[216:219], v[70:73]
	v_mfma_f32_16x16x32_bf16 v[66:69], v[172:175], v[216:219], v[66:69]
	v_mfma_f32_16x16x32_bf16 v[118:121], v[168:171], v[184:187], v[118:121]
	v_mfma_f32_16x16x32_bf16 v[114:117], v[176:179], v[184:187], v[114:117]
	v_mfma_f32_16x16x32_bf16 v[102:105], v[168:171], v[204:207], v[102:105]
	v_mfma_f32_16x16x32_bf16 v[98:101], v[176:179], v[204:207], v[98:101]
	v_mfma_f32_16x16x32_bf16 v[86:89], v[168:171], v[212:215], v[86:89]
	v_mfma_f32_16x16x32_bf16 v[82:85], v[176:179], v[212:215], v[82:85]
	v_mfma_f32_16x16x32_bf16 v[70:73], v[168:171], v[220:223], v[70:73]
	v_mfma_f32_16x16x32_bf16 v[66:69], v[176:179], v[220:223], v[66:69]
	s_setprio 0
	s_barrier
	s_add_i32 s58, s74, s5
	v_lshl_add_u64 v[142:143], v[142:143], 0, s[24:25]
	s_mov_b32 m0, s58
	s_nop 0
	global_load_lds_dwordx4 v[142:143], off
	v_lshl_add_u64 v[142:143], v[188:189], 0, s[24:25]
	s_add_i32 m0, s58, 0x2000
	s_add_i32 s58, s75, s5
	global_load_lds_dwordx4 v[142:143], off
	v_lshl_add_u64 v[142:143], v[224:225], 0, s[24:25]
	s_mov_b32 m0, s58
	s_nop 0
	global_load_lds_dwordx4 v[142:143], off
	v_lshl_add_u64 v[142:143], v[226:227], 0, s[24:25]
	s_add_i32 m0, s58, 0x2000
	s_nop 0
	global_load_lds_dwordx4 v[142:143], off
	ds_read_b128 v[180:183], v147 offset:49152
	ds_read_b128 v[184:187], v147 offset:50176
	ds_read_b128 v[200:203], v147 offset:51200
	ds_read_b128 v[204:207], v147 offset:52224
	ds_read_b128 v[208:211], v147 offset:53248
	ds_read_b128 v[212:215], v147 offset:54272
	ds_read_b128 v[216:219], v147 offset:55296
	ds_read_b128 v[220:223], v147 offset:56320
	s_waitcnt vmcnt(6)
	s_waitcnt lgkmcnt(0)
	s_barrier
	s_setprio 1
	s_waitcnt lgkmcnt(0)
	v_mfma_f32_16x16x32_bf16 v[62:65], v[148:151], v[180:183], v[62:65]
	v_mfma_f32_16x16x32_bf16 v[58:61], v[156:159], v[180:183], v[58:61]
	v_mfma_f32_16x16x32_bf16 v[46:49], v[148:151], v[200:203], v[46:49]
	v_mfma_f32_16x16x32_bf16 v[42:45], v[156:159], v[200:203], v[42:45]
	v_mfma_f32_16x16x32_bf16 v[30:33], v[148:151], v[208:211], v[30:33]
	v_mfma_f32_16x16x32_bf16 v[26:29], v[156:159], v[208:211], v[26:29]
	v_mfma_f32_16x16x32_bf16 v[14:17], v[148:151], v[216:219], v[14:17]
	v_mfma_f32_16x16x32_bf16 v[10:13], v[156:159], v[216:219], v[10:13]
	v_mfma_f32_16x16x32_bf16 v[62:65], v[152:155], v[184:187], v[62:65]
	v_mfma_f32_16x16x32_bf16 v[58:61], v[160:163], v[184:187], v[58:61]
	v_mfma_f32_16x16x32_bf16 v[46:49], v[152:155], v[204:207], v[46:49]
	v_mfma_f32_16x16x32_bf16 v[42:45], v[160:163], v[204:207], v[42:45]
	v_mfma_f32_16x16x32_bf16 v[30:33], v[152:155], v[212:215], v[30:33]
	v_mfma_f32_16x16x32_bf16 v[26:29], v[160:163], v[212:215], v[26:29]
	v_mfma_f32_16x16x32_bf16 v[14:17], v[152:155], v[220:223], v[14:17]
	v_mfma_f32_16x16x32_bf16 v[10:13], v[160:163], v[220:223], v[10:13]
	s_setprio 0
	s_setprio 1
	v_mfma_f32_16x16x32_bf16 v[54:57], v[164:167], v[180:183], v[54:57]
	v_mfma_f32_16x16x32_bf16 v[50:53], v[172:175], v[180:183], v[50:53]
	v_mfma_f32_16x16x32_bf16 v[38:41], v[164:167], v[200:203], v[38:41]
	v_mfma_f32_16x16x32_bf16 v[34:37], v[172:175], v[200:203], v[34:37]
	v_mfma_f32_16x16x32_bf16 v[22:25], v[164:167], v[208:211], v[22:25]
	v_mfma_f32_16x16x32_bf16 v[18:21], v[172:175], v[208:211], v[18:21]
	v_mfma_f32_16x16x32_bf16 v[6:9], v[164:167], v[216:219], v[6:9]
	v_mfma_f32_16x16x32_bf16 v[2:5], v[172:175], v[216:219], v[2:5]
	v_mfma_f32_16x16x32_bf16 v[54:57], v[168:171], v[184:187], v[54:57]
	v_mfma_f32_16x16x32_bf16 v[50:53], v[176:179], v[184:187], v[50:53]
	v_mfma_f32_16x16x32_bf16 v[38:41], v[168:171], v[204:207], v[38:41]
	v_mfma_f32_16x16x32_bf16 v[34:37], v[176:179], v[204:207], v[34:37]
	v_mfma_f32_16x16x32_bf16 v[22:25], v[168:171], v[212:215], v[22:25]
	v_mfma_f32_16x16x32_bf16 v[18:21], v[176:179], v[212:215], v[18:21]
	v_mfma_f32_16x16x32_bf16 v[6:9], v[168:171], v[220:223], v[6:9]
	v_mfma_f32_16x16x32_bf16 v[2:5], v[176:179], v[220:223], v[2:5]
	s_setprio 0
	s_barrier
	s_add_u32 s56, s56, 0x100
	s_addc_u32 s57, s57, 0
	s_add_u32 s67, s67, 0x100
	s_addc_u32 s72, s72, 0
	s_cmp_ge_i32 s73, s60
	s_mov_b32 s58, s73
	s_cbranch_scc0 .LBB0_211
	v_readlane_b32 s74, v236, 30
	v_readlane_b32 s75, v236, 31
	v_readlane_b32 s73, v236, 32
	s_mov_b32 s78, s76
